# attention DMA issue block hand-written: straight-line for the always-valid pieces, extras of waves 0/1 out of line
# speedup vs baseline: 1.0524x; 1.0055x over previous
.Latt_diff_p0:
.LBB0_107:
	s_add_i32 s30, s52, 2
	s_cmp_ge_u32 s30, s21
	s_cselect_b64 s[46:47], -1, 0
	s_cbranch_scc1 .LBB0_116
	s_cmp_lt_u32 s52, 2
	s_cselect_b32 s48, s45, s43
	s_mul_i32 s55, s50, 0x2400
	s_add_i32 s56, s55, s41
	s_mov_b32 m0, s56
	v_lshl_add_u32 v244, s48, 12, v153
	global_load_lds_dwordx4 v244, s[18:19]
	s_ashr_i32 s49, s48, 31
	s_lshl_b64 s[30:31], s[48:49], 1
	s_add_u32 s30, s39, s30
	s_addc_u32 s31, s42, s31
	s_add_i32 s55, s55, s56
	s_add_i32 m0, s55, 0x6c00
	v_lshl_add_u64 v[244:245], s[30:31], 0, v[150:151]
	global_load_lds_dwordx4 v[244:245], off
	s_add_i32 m0, s55, 0x8c00
	v_lshl_add_u64 v[244:245], s[30:31], 0, v[148:149]
	global_load_lds_dwordx4 v[244:245], off
	s_and_b64 vcc, exec, s[14:15]
	s_cbranch_vccz .Latt_diff_dmax

.Latt_diff_dmax:
	s_add_i32 m0, s55, 0xac00
	v_lshl_add_u64 v[244:245], s[30:31], 0, v[146:147]
	global_load_lds_dwordx4 v[244:245], off
	s_and_b64 vcc, exec, s[8:9]
	s_cbranch_vccnz .LBB0_116
	s_add_i32 m0, s56, 0x2000
	v_lshl_add_u32 v244, s48, 12, v155
	global_load_lds_dwordx4 v244, s[18:19]
	s_branch .LBB0_116

.Latt_mla_p0:
.LBB0_178:
	s_add_i32 s30, s55, 2
	s_cmp_ge_u32 s30, s20
	s_cselect_b64 s[60:61], -1, 0
	s_cbranch_scc1 .LBB0_191
	s_cmp_lt_u32 s55, 2
	s_cselect_b32 s62, s51, s49
	s_mul_i32 s57, s52, 0x6400
	s_add_i32 s57, s57, s42
	s_mov_b32 m0, s57
	v_mad_u32_u24 v250, s62, v237, v222
	global_load_lds_dwordx4 v250, s[2:3]
	s_add_i32 m0, s57, 0x2000
	v_mad_u32_u24 v250, s62, v239, v224
	global_load_lds_dwordx4 v250, s[2:3]
	s_add_i32 m0, s57, 0x4000
	v_mad_u32_u24 v250, s62, v241, v226
	global_load_lds_dwordx4 v250, s[2:3]
	s_ashr_i32 s63, s62, 31
	s_lshl_b64 s[30:31], s[62:63], 1
	s_add_u32 s30, s21, s30
	s_addc_u32 s31, s43, s31
	s_mul_i32 s63, s52, 0x4800
	s_add_i32 s63, s63, s42
	s_add_i32 m0, s63, 0x12c00
	v_lshl_add_u64 v[250:251], s[30:31], 0, v[202:203]
	global_load_lds_dwordx4 v[250:251], off
	s_add_i32 m0, s63, 0x14c00
	v_lshl_add_u64 v[250:251], s[30:31], 0, v[200:201]
	global_load_lds_dwordx4 v[250:251], off
	s_and_b64 vcc, exec, s[18:19]
	s_cbranch_vccz .Latt_mla_dmax

.Latt_mla_dmax:
	s_add_i32 m0, s63, 0x16c00
	v_lshl_add_u64 v[250:251], s[30:31], 0, v[198:199]
	global_load_lds_dwordx4 v[250:251], off
	s_and_b64 vcc, exec, s[12:13]
	s_cbranch_vccnz .LBB0_191
	s_add_i32 m0, s57, 0x6000
	v_mad_u32_u24 v250, s62, v243, v228
	global_load_lds_dwordx4 v250, s[2:3]
	s_branch .LBB0_191
